# speedup vs baseline: 1.0598x; 1.0009x over previous
; DEVI int nblk() { int n = NBLK; asm volatile("" : "+s"(n)); return n; }
; DEVI int otid() { int t = threadIdx.x; asm volatile("" : "+v"(t)); return t; }
; #define WAIT_V0() asm volatile("s_waitcnt vmcnt(0)" ::: "memory")
; #define G_STAGE(buf, kt) do { _Pragma("unroll") for (int i = 0; i < 4; ++i) { \
;     __builtin_amdgcn_global_load_lds((const unsigned*)(A + oA[i] + (long)(kt) * BK), (unsigned*)(G_SA(buf) + wid * 1024 + i * 8192), 16, 0, 0); \
;     __builtin_amdgcn_global_load_lds((const unsigned*)(B + oB[i] + (long)(kt) * BK), (unsigned*)(G_SB(buf) + wid * 1024 + i * 8192), 16, 0, 0); } } while (0)
; DEVI FcT fc_dec(int t) { FcT d; d.s = t >> 10; d.tile = t & 1023; d.sb = seq_base(d.s); d.K2 = 2 * (seq_len(d.s) >> 7); return d; }
; template <class RA, class RB, class EPI>
; DEVI void gemm_tile(RA rowA, RB rowB, const bfr* __restrict__ A, const bfr* __restrict__ B, int K, char* shm, EPI epi,
;                     bool pre, bool hn, RA rowA_n, RB rowB_n, const bfr* __restrict__ A_n, const bfr* __restrict__ B_n) {
;   const int tid = otid(), wid = tid >> 6, lane = tid & 63, wr = wid >> 2, wc = wid & 3, fr = lane & 15, fq = lane >> 4;
;   long oA[4], oB[4];
; #pragma unroll
;   for (int i = 0; i < 4; ++i) { int R, C; stage_rc(wid * 1024 + i * 8192 + lane * 16, R, C); oA[i] = rowA(R) + C; oB[i] = rowB(R) + C; }
;   f32x4 acc[8][4];
; #pragma unroll
;   for (int m = 0; m < 8; ++m)
; #pragma unroll
;     for (int n = 0; n < 4; ++n) acc[m][n] = f32x4{0.f, 0.f, 0.f, 0.f};
;     ...
;   const int nt = K / BK;
;   if (!pre) G_STAGE(0, 0);
;   WAIT_V0(); __syncthreads();
; DEVI void phase_fnet_c(const bfr* D2, const bfr* MC128, const bfr* MC64, bfr* f, char* shm) {
;     ...
;     const int tn = t + nblk(); const bool hn = tn < 3072; const FcT nx = fc_dec(hn ? tn : 0);
;     const int s = c.s, tile = c.tile, sb = c.sb, K2 = c.K2, N2 = K2 >> 1;
;     const bfr* D2s = D2 + (long)sb * 4096; const bfr* MC = (s == 0) ? MC128 : MC64;
;     const int k1 = tile >> 3, ch0 = (tile & 7) * 256;
;     const float scl = (s == 0) ? (1.f / 2048.f) : 6.905339660024878e-4f;
;     gemm_tile(mkA(c), mkB(c), D2s, MC, K2, shm,
.LBB0_296:
	v_bfe_u32 v0, v164, 6, 2
	s_cmp_eq_u32 s57, 0
	s_cselect_b32 s100, 2, 1
	v_readfirstlane_b32 s101, v0
	s_nop 3
	s_cmp_ge_u32 s101, s100
	s_cselect_b32 s100, 1, 0
	s_mov_b32 s58, s91
	s_movk_i32 s8, 0x100
	s_lshl_b64 s[0:1], s[58:59], 13
	v_mov_b32_e32 v0, v164
	s_cmp_eq_u32 s57, 0
	s_cselect_b64 s[4:5], -1, 0
	v_and_b32_e32 v8, 15, v0
	v_lshlrev_b32_e32 v10, 2, v0
	v_lshlrev_b32_e32 v1, 4, v0
	v_and_b32_e32 v2, 32, v0
	v_and_b32_e32 v9, 48, v0
	v_lshlrev_b32_e32 v8, 6, v8
	v_and_b32_e32 v10, 32, v10
	s_and_b64 s[10:11], s[4:5], exec
	v_and_b32_e32 v144, 0xfffffc00, v1
	v_lshrrev_b32_e32 v3, 1, v0
	v_bitop3_b32 v2, v1, v2, 48 bitop3:0x6c
	v_add_u32_e32 v6, 0x2000, v1
	v_add_u32_e32 v7, 0x4000, v1
	v_add_u32_e32 v1, 0x6000, v1
	v_bitop3_b32 v150, v8, v10, v9 bitop3:0x36
	v_lshlrev_b32_e32 v8, 6, v0
	s_cselect_b32 s11, s68, s72
	s_cselect_b32 s28, s35, s69
	s_lshl_b32 s7, s83, 8
	v_lshrrev_b32_e32 v4, 2, v0
	v_bfe_u32 v145, v0, 2, 4
	v_and_b32_e32 v3, 32, v3
	v_lshrrev_b32_e32 v2, 1, v2
	v_ashrrev_i32_e32 v5, 3, v0
	v_ashrrev_i32_e32 v1, 7, v1
	s_lshr_b32 s10, s2, 6
	v_and_b32_e32 v151, 0xffffc000, v8
	v_and_b32_e32 v8, 0x3c0, v8
	v_lshlrev_b32_e32 v0, 7, v0
	v_bitop3_b32 v153, v8, v10, v9 bitop3:0x36
	v_and_b32_e32 v160, 0x6000, v0
	v_or_b32_e32 v0, v2, v3
	s_add_u32 s28, s28, 0x80
	v_bfi_b32 v8, -16, v1, v4
	v_lshlrev_b32_e32 v166, 1, v0
	s_addc_u32 s29, s11, 0
	v_ashrrev_i32_e32 v0, 31, v8
	v_and_b32_e32 v146, -16, v1
	v_alignbit_b32 v3, v0, v8, 31
	v_lshlrev_b32_e32 v2, 1, v8
	v_mov_b64_e32 v[0:1], s[28:29]
	v_mad_u64_u32 v[128:129], s[28:29], v2, s2, v[0:1]
	v_ashrrev_i32_e32 v7, 7, v7
	v_mov_b32_e32 v2, v129
	v_and_b32_e32 v147, -16, v7
	v_mad_u64_u32 v[2:3], s[28:29], v3, s2, v[2:3]
	v_bfi_b32 v7, -16, v7, v4
	v_mov_b32_e32 v129, v2
	v_ashrrev_i32_e32 v2, 31, v7
	v_alignbit_b32 v3, v2, v7, 31
	v_lshlrev_b32_e32 v2, 1, v7
	v_mad_u64_u32 v[130:131], s[28:29], v2, s2, v[0:1]
	v_ashrrev_i32_e32 v6, 7, v6
	v_mov_b32_e32 v2, v131
	v_and_b32_e32 v148, -16, v6
	v_mad_u64_u32 v[2:3], s[28:29], v3, s2, v[2:3]
	v_bfi_b32 v6, -16, v6, v4
	v_mov_b32_e32 v131, v2
	v_ashrrev_i32_e32 v2, 31, v6
	v_alignbit_b32 v3, v2, v6, 31
	v_lshlrev_b32_e32 v2, 1, v6
	v_mad_u64_u32 v[132:133], s[28:29], v2, s2, v[0:1]
	v_mov_b32_e32 v2, v133
	v_mad_u64_u32 v[2:3], s[28:29], v3, s2, v[2:3]
	v_bfi_b32 v4, -16, v5, v4
	v_lshlrev_b32_e32 v3, 1, v4
	v_mov_b32_e32 v133, v2
	v_ashrrev_i32_e32 v2, 31, v4
	v_mad_u64_u32 v[134:135], s[28:29], v3, s2, v[0:1]
	v_alignbit_b32 v2, v2, v4, 31
	v_mov_b32_e32 v0, v135
	v_mad_u64_u32 v[0:1], s[28:29], v2, s2, v[0:1]
	v_mov_b32_e32 v135, v0
	v_add_u32_e32 v0, s7, v8
	s_add_u32 s0, s73, s0
	v_ashrrev_i32_e32 v1, 31, v0
	s_addc_u32 s1, s82, s1
	v_alignbit_b32 v3, v1, v0, 31
	v_lshlrev_b32_e32 v2, 1, v0
	v_mov_b64_e32 v[0:1], s[0:1]
	v_mad_u64_u32 v[136:137], s[0:1], v2, s2, v[0:1]
	v_mov_b32_e32 v2, v137
	v_mad_u64_u32 v[2:3], s[0:1], v3, s2, v[2:3]
	v_mov_b32_e32 v137, v2
	v_add_u32_e32 v2, s7, v7
	v_ashrrev_i32_e32 v3, 31, v2
	v_alignbit_b32 v3, v3, v2, 31
	v_lshlrev_b32_e32 v2, 1, v2
	v_mad_u64_u32 v[138:139], s[0:1], v2, s2, v[0:1]
	v_mov_b32_e32 v2, v139
	v_mad_u64_u32 v[2:3], s[0:1], v3, s2, v[2:3]
	v_mov_b32_e32 v139, v2
	v_add_u32_e32 v2, s7, v6
	v_ashrrev_i32_e32 v3, 31, v2
	v_alignbit_b32 v3, v3, v2, 31
	v_lshlrev_b32_e32 v2, 1, v2
	v_mad_u64_u32 v[140:141], s[0:1], v2, s2, v[0:1]
	v_mov_b32_e32 v2, v141
	v_mad_u64_u32 v[2:3], s[0:1], v3, s2, v[2:3]
	v_mov_b32_e32 v141, v2
	v_add_u32_e32 v2, s7, v4
	v_ashrrev_i32_e32 v3, 31, v2
	v_alignbit_b32 v3, v3, v2, 31
	v_lshlrev_b32_e32 v2, 1, v2
	v_mad_u64_u32 v[142:143], s[0:1], v2, s2, v[0:1]
	v_mov_b32_e32 v0, v143
	s_waitcnt vmcnt(0)
	v_mad_u64_u32 v[0:1], s[0:1], v3, s2, v[0:1]
	v_mov_b32_e32 v143, v0
	v_mov_b32_e32 v0, 0
	s_mov_b32 s6, s83
	s_mov_b32 s9, 0
	v_and_b32_e32 v149, -16, v5
	v_or_b32_e32 v152, 0x800, v151
	v_or_b32_e32 v154, 0x1000, v151
	v_or_b32_e32 v155, 0x1800, v151
	v_or_b32_e32 v156, 0x2000, v151
	v_or_b32_e32 v157, 0x2800, v151
	v_or_b32_e32 v158, 0x3000, v151
	v_or_b32_e32 v159, 0x3800, v151
	v_mov_b32_e32 v1, v0
	v_mov_b32_e32 v2, v0
	v_mov_b32_e32 v3, v0
	v_mov_b32_e32 v8, v0
	v_mov_b32_e32 v9, v0
	v_mov_b32_e32 v10, v0
	v_mov_b32_e32 v11, v0
	v_mov_b32_e32 v16, v0
	v_mov_b32_e32 v17, v0
	v_mov_b32_e32 v18, v0
	v_mov_b32_e32 v19, v0
	v_mov_b32_e32 v24, v0
	v_mov_b32_e32 v25, v0
	v_mov_b32_e32 v26, v0
	v_mov_b32_e32 v27, v0
	v_mov_b32_e32 v4, v0
	v_mov_b32_e32 v5, v0
	v_mov_b32_e32 v6, v0
	v_mov_b32_e32 v7, v0
	v_mov_b32_e32 v12, v0
	v_mov_b32_e32 v13, v0
	v_mov_b32_e32 v14, v0
	v_mov_b32_e32 v15, v0
	v_mov_b32_e32 v20, v0
	v_mov_b32_e32 v21, v0
	v_mov_b32_e32 v22, v0
	v_mov_b32_e32 v23, v0
	v_mov_b32_e32 v28, v0
	v_mov_b32_e32 v29, v0
	v_mov_b32_e32 v30, v0
	v_mov_b32_e32 v31, v0
	v_mov_b32_e32 v32, v0
	v_mov_b32_e32 v33, v0
	v_mov_b32_e32 v34, v0
	v_mov_b32_e32 v35, v0
	v_mov_b32_e32 v40, v0
	v_mov_b32_e32 v41, v0
	v_mov_b32_e32 v42, v0
	v_mov_b32_e32 v43, v0
	v_mov_b32_e32 v48, v0
	v_mov_b32_e32 v49, v0
	v_mov_b32_e32 v50, v0
	v_mov_b32_e32 v51, v0
	v_mov_b32_e32 v56, v0
	v_mov_b32_e32 v57, v0
	v_mov_b32_e32 v58, v0
	v_mov_b32_e32 v59, v0
	v_mov_b32_e32 v36, v0
	v_mov_b32_e32 v37, v0
	v_mov_b32_e32 v38, v0
	v_mov_b32_e32 v39, v0
	v_mov_b32_e32 v44, v0
	v_mov_b32_e32 v45, v0
	v_mov_b32_e32 v46, v0
	v_mov_b32_e32 v47, v0
	v_mov_b32_e32 v52, v0
	v_mov_b32_e32 v53, v0
	v_mov_b32_e32 v54, v0
	v_mov_b32_e32 v55, v0
	v_mov_b32_e32 v60, v0
	v_mov_b32_e32 v61, v0
	v_mov_b32_e32 v62, v0
	v_mov_b32_e32 v63, v0
	v_mov_b32_e32 v64, v0
	v_mov_b32_e32 v65, v0
	v_mov_b32_e32 v66, v0
	v_mov_b32_e32 v67, v0
	v_mov_b32_e32 v72, v0
	v_mov_b32_e32 v73, v0
	v_mov_b32_e32 v74, v0
	v_mov_b32_e32 v75, v0
	v_mov_b32_e32 v80, v0
	v_mov_b32_e32 v81, v0
	v_mov_b32_e32 v82, v0
	v_mov_b32_e32 v83, v0
	v_mov_b32_e32 v88, v0
	v_mov_b32_e32 v89, v0
	v_mov_b32_e32 v90, v0
	v_mov_b32_e32 v91, v0
	v_mov_b32_e32 v68, v0
	v_mov_b32_e32 v69, v0
	v_mov_b32_e32 v70, v0
	v_mov_b32_e32 v71, v0
	v_mov_b32_e32 v76, v0
	v_mov_b32_e32 v77, v0
	v_mov_b32_e32 v78, v0
	v_mov_b32_e32 v79, v0
	v_mov_b32_e32 v84, v0
	v_mov_b32_e32 v85, v0
	v_mov_b32_e32 v86, v0
	v_mov_b32_e32 v87, v0
	v_mov_b32_e32 v92, v0
	v_mov_b32_e32 v93, v0
	v_mov_b32_e32 v94, v0
	v_mov_b32_e32 v95, v0
	v_mov_b32_e32 v96, v0
	v_mov_b32_e32 v97, v0
	v_mov_b32_e32 v98, v0
	v_mov_b32_e32 v99, v0
	v_mov_b32_e32 v104, v0
	v_mov_b32_e32 v105, v0
	v_mov_b32_e32 v106, v0
	v_mov_b32_e32 v107, v0
	v_mov_b32_e32 v112, v0
	v_mov_b32_e32 v113, v0
	v_mov_b32_e32 v114, v0
	v_mov_b32_e32 v115, v0
	v_mov_b32_e32 v120, v0
	v_mov_b32_e32 v121, v0
	v_mov_b32_e32 v122, v0
	v_mov_b32_e32 v123, v0
	v_mov_b32_e32 v100, v0
	v_mov_b32_e32 v101, v0
	v_mov_b32_e32 v102, v0
	v_mov_b32_e32 v103, v0
	v_mov_b32_e32 v108, v0
	v_mov_b32_e32 v109, v0
	v_mov_b32_e32 v110, v0
	v_mov_b32_e32 v111, v0
	v_mov_b32_e32 v116, v0
	v_mov_b32_e32 v117, v0
	v_mov_b32_e32 v118, v0
	v_mov_b32_e32 v119, v0
	v_mov_b32_e32 v124, v0
	v_mov_b32_e32 v125, v0
	v_mov_b32_e32 v126, v0
	v_mov_b32_e32 v127, v0
	s_waitcnt vmcnt(0) lgkmcnt(0)
	s_barrier
; #define WAIT_V0() asm volatile("s_waitcnt vmcnt(0)" ::: "memory")
; #define SCHEDB() __builtin_amdgcn_sched_barrier(0)
; #define G_STAGE(buf, kt) do { _Pragma("unroll") for (int i = 0; i < 4; ++i) { \
;     __builtin_amdgcn_global_load_lds((const unsigned*)(A + oA[i] + (long)(kt) * BK), (unsigned*)(G_SA(buf) + wid * 1024 + i * 8192), 16, 0, 0); \
;     __builtin_amdgcn_global_load_lds((const unsigned*)(B + oB[i] + (long)(kt) * BK), (unsigned*)(G_SB(buf) + wid * 1024 + i * 8192), 16, 0, 0); } } while (0)
; template <class RA, class RB, class EPI>
; DEVI void gemm_tile(RA rowA, RB rowB, const bfr* __restrict__ A, const bfr* __restrict__ B, int K, char* shm, EPI epi,
;                     bool pre, bool hn, RA rowA_n, RB rowB_n, const bfr* __restrict__ A_n, const bfr* __restrict__ B_n) {
;     ...
;   for (int t = 0; t < nt; ++t) {
;     const int cur = t & 1;
;     if (t + 1 < nt) G_STAGE(cur ^ 1, t + 1);
; #pragma unroll
;     for (int ks = 0; ks < 2; ++ks) {
;       bf16x8 At[8], Bf[4];
; #pragma unroll
;       for (int m = 0; m < 8; ++m) At[m] = *(const bf16x8*)(G_SA(cur) + lds_byte(wr * 128 + m * 16 + fr, ks * 32 + fq * 8));
; #pragma unroll
;       for (int n = 0; n < 4; ++n) Bf[n] = *(const bf16x8*)(G_SB(cur) + lds_byte(wc * 64 + n * 16 + fr, ks * 32 + fq * 8));
; #pragma unroll
;       for (int m = 0; m < 8; ++m)
; #pragma unroll
;         for (int n = 0; n < 4; ++n) acc[m][n] = __builtin_amdgcn_mfma_f32_16x16x32_bf16(At[m], Bf[n], acc[m][n], 0, 0, 0);
;       SCHEDB();
;     }
;     WAIT_V0(); __syncthreads();
;   }
	s_branch .LBB0_298
.LBB0_297:
	s_cmp_lg_u32 s100, 0
	s_cbranch_scc1 .Lfc_skip
	v_add3_u32 v161, s11, v150, v151
	ds_read_b128 v[170:173], v161
	v_add3_u32 v162, s11, v150, v160
	ds_read_b128 v[174:177], v162 offset:32768
	ds_read_b128 v[178:181], v162 offset:34816
	ds_read_b128 v[182:185], v162 offset:36864
	ds_read_b128 v[186:189], v162 offset:38912
	v_add3_u32 v163, s11, v153, v152
	v_add3_u32 v190, s11, v153, v154
	v_add3_u32 v191, s11, v153, v155
	s_waitcnt lgkmcnt(0)
	v_mfma_f32_16x16x32_bf16 v[124:127], v[170:173], v[174:177], v[124:127]
	v_add3_u32 v192, s11, v153, v156
	v_add3_u32 v193, s11, v153, v157
	v_add3_u32 v194, s11, v153, v158
	v_mfma_f32_16x16x32_bf16 v[116:119], v[170:173], v[178:181], v[116:119]
	v_add3_u32 v196, s11, v153, v159
	v_mfma_f32_16x16x32_bf16 v[108:111], v[170:173], v[182:185], v[108:111]
	v_mfma_f32_16x16x32_bf16 v[100:103], v[170:173], v[186:189], v[100:103]
	ds_read_b128 v[170:173], v163
	s_waitcnt lgkmcnt(0)
	v_mfma_f32_16x16x32_bf16 v[120:123], v[170:173], v[174:177], v[120:123]
	v_mfma_f32_16x16x32_bf16 v[112:115], v[170:173], v[178:181], v[112:115]
	v_mfma_f32_16x16x32_bf16 v[104:107], v[170:173], v[182:185], v[104:107]
	v_mfma_f32_16x16x32_bf16 v[96:99], v[170:173], v[186:189], v[96:99]
	ds_read_b128 v[170:173], v190
	s_waitcnt lgkmcnt(0)
	v_mfma_f32_16x16x32_bf16 v[92:95], v[170:173], v[174:177], v[92:95]
	v_mfma_f32_16x16x32_bf16 v[84:87], v[170:173], v[178:181], v[84:87]
	v_mfma_f32_16x16x32_bf16 v[76:79], v[170:173], v[182:185], v[76:79]
	v_mfma_f32_16x16x32_bf16 v[68:71], v[170:173], v[186:189], v[68:71]
	ds_read_b128 v[170:173], v191
	s_waitcnt lgkmcnt(0)
	v_mfma_f32_16x16x32_bf16 v[88:91], v[170:173], v[174:177], v[88:91]
	v_mfma_f32_16x16x32_bf16 v[80:83], v[170:173], v[178:181], v[80:83]
	v_mfma_f32_16x16x32_bf16 v[72:75], v[170:173], v[182:185], v[72:75]
	v_mfma_f32_16x16x32_bf16 v[64:67], v[170:173], v[186:189], v[64:67]
	ds_read_b128 v[170:173], v192
	s_waitcnt lgkmcnt(0)
	v_mfma_f32_16x16x32_bf16 v[60:63], v[170:173], v[174:177], v[60:63]
	v_mfma_f32_16x16x32_bf16 v[52:55], v[170:173], v[178:181], v[52:55]
	v_mfma_f32_16x16x32_bf16 v[44:47], v[170:173], v[182:185], v[44:47]
	v_mfma_f32_16x16x32_bf16 v[36:39], v[170:173], v[186:189], v[36:39]
	ds_read_b128 v[170:173], v193
	s_waitcnt lgkmcnt(0)
	v_mfma_f32_16x16x32_bf16 v[56:59], v[170:173], v[174:177], v[56:59]
	v_mfma_f32_16x16x32_bf16 v[48:51], v[170:173], v[178:181], v[48:51]
	v_mfma_f32_16x16x32_bf16 v[40:43], v[170:173], v[182:185], v[40:43]
	v_mfma_f32_16x16x32_bf16 v[32:35], v[170:173], v[186:189], v[32:35]
	ds_read_b128 v[170:173], v194
	s_waitcnt lgkmcnt(0)
	v_mfma_f32_16x16x32_bf16 v[28:31], v[170:173], v[174:177], v[28:31]
	v_mfma_f32_16x16x32_bf16 v[20:23], v[170:173], v[178:181], v[20:23]
	v_mfma_f32_16x16x32_bf16 v[12:15], v[170:173], v[182:185], v[12:15]
	v_mfma_f32_16x16x32_bf16 v[4:7], v[170:173], v[186:189], v[4:7]
	ds_read_b128 v[170:173], v196
	s_waitcnt lgkmcnt(0)
	v_mfma_f32_16x16x32_bf16 v[24:27], v[170:173], v[174:177], v[24:27]
	v_mfma_f32_16x16x32_bf16 v[16:19], v[170:173], v[178:181], v[16:19]
	v_mfma_f32_16x16x32_bf16 v[8:11], v[170:173], v[182:185], v[8:11]
	v_mfma_f32_16x16x32_bf16 v[0:3], v[170:173], v[186:189], v[0:3]
	ds_read_b128 v[170:173], v161 offset:1024
	ds_read_b128 v[174:177], v162 offset:33792
	ds_read_b128 v[178:181], v162 offset:35840
	ds_read_b128 v[182:185], v162 offset:37888
	ds_read_b128 v[186:189], v162 offset:39936
	s_waitcnt lgkmcnt(0)
	v_mfma_f32_16x16x32_bf16 v[124:127], v[170:173], v[174:177], v[124:127]
	v_mfma_f32_16x16x32_bf16 v[116:119], v[170:173], v[178:181], v[116:119]
	v_mfma_f32_16x16x32_bf16 v[108:111], v[170:173], v[182:185], v[108:111]
	v_mfma_f32_16x16x32_bf16 v[100:103], v[170:173], v[186:189], v[100:103]
	ds_read_b128 v[170:173], v163 offset:1024
	s_waitcnt lgkmcnt(0)
	v_mfma_f32_16x16x32_bf16 v[120:123], v[170:173], v[174:177], v[120:123]
	v_mfma_f32_16x16x32_bf16 v[112:115], v[170:173], v[178:181], v[112:115]
	v_mfma_f32_16x16x32_bf16 v[104:107], v[170:173], v[182:185], v[104:107]
	v_mfma_f32_16x16x32_bf16 v[96:99], v[170:173], v[186:189], v[96:99]
	ds_read_b128 v[170:173], v190 offset:1024
	s_waitcnt lgkmcnt(0)
	v_mfma_f32_16x16x32_bf16 v[92:95], v[170:173], v[174:177], v[92:95]
	v_mfma_f32_16x16x32_bf16 v[84:87], v[170:173], v[178:181], v[84:87]
	v_mfma_f32_16x16x32_bf16 v[76:79], v[170:173], v[182:185], v[76:79]
	v_mfma_f32_16x16x32_bf16 v[68:71], v[170:173], v[186:189], v[68:71]
	ds_read_b128 v[170:173], v191 offset:1024
	s_waitcnt lgkmcnt(0)
	v_mfma_f32_16x16x32_bf16 v[88:91], v[170:173], v[174:177], v[88:91]
	v_mfma_f32_16x16x32_bf16 v[80:83], v[170:173], v[178:181], v[80:83]
	v_mfma_f32_16x16x32_bf16 v[72:75], v[170:173], v[182:185], v[72:75]
	v_mfma_f32_16x16x32_bf16 v[64:67], v[170:173], v[186:189], v[64:67]
	ds_read_b128 v[170:173], v192 offset:1024
	s_waitcnt lgkmcnt(0)
	v_mfma_f32_16x16x32_bf16 v[60:63], v[170:173], v[174:177], v[60:63]
	v_mfma_f32_16x16x32_bf16 v[52:55], v[170:173], v[178:181], v[52:55]
	v_mfma_f32_16x16x32_bf16 v[44:47], v[170:173], v[182:185], v[44:47]
	v_mfma_f32_16x16x32_bf16 v[36:39], v[170:173], v[186:189], v[36:39]
	ds_read_b128 v[170:173], v193 offset:1024
	s_waitcnt lgkmcnt(0)
	v_mfma_f32_16x16x32_bf16 v[56:59], v[170:173], v[174:177], v[56:59]
	v_mfma_f32_16x16x32_bf16 v[48:51], v[170:173], v[178:181], v[48:51]
	v_mfma_f32_16x16x32_bf16 v[40:43], v[170:173], v[182:185], v[40:43]
	v_mfma_f32_16x16x32_bf16 v[32:35], v[170:173], v[186:189], v[32:35]
	ds_read_b128 v[170:173], v194 offset:1024
	s_waitcnt lgkmcnt(0)
	v_mfma_f32_16x16x32_bf16 v[28:31], v[170:173], v[174:177], v[28:31]
	v_mfma_f32_16x16x32_bf16 v[20:23], v[170:173], v[178:181], v[20:23]
	v_mfma_f32_16x16x32_bf16 v[12:15], v[170:173], v[182:185], v[12:15]
	v_mfma_f32_16x16x32_bf16 v[4:7], v[170:173], v[186:189], v[4:7]
	ds_read_b128 v[170:173], v196 offset:1024
	s_waitcnt lgkmcnt(0)
	v_mfma_f32_16x16x32_bf16 v[24:27], v[170:173], v[174:177], v[24:27]
	v_mfma_f32_16x16x32_bf16 v[16:19], v[170:173], v[178:181], v[16:19]
	v_mfma_f32_16x16x32_bf16 v[8:11], v[170:173], v[182:185], v[8:11]
	v_mfma_f32_16x16x32_bf16 v[0:3], v[170:173], v[186:189], v[0:3]
.Lfc_skip:
	s_waitcnt vmcnt(0)
	v_lshl_add_u64 v[128:129], v[128:129], 0, s[62:63]
	v_lshl_add_u64 v[130:131], v[130:131], 0, s[62:63]
	v_lshl_add_u64 v[132:133], v[132:133], 0, s[62:63]
	v_lshl_add_u64 v[134:135], v[134:135], 0, s[62:63]
	v_lshl_add_u64 v[136:137], v[136:137], 0, s[62:63]
	v_lshl_add_u64 v[138:139], v[138:139], 0, s[62:63]
	v_lshl_add_u64 v[140:141], v[140:141], 0, s[62:63]
	s_cmp_eq_u32 s10, s9
	v_lshl_add_u64 v[142:143], v[142:143], 0, s[62:63]
	s_waitcnt vmcnt(0)
	s_barrier
	s_cbranch_scc1 .LBB0_302
